# static s_setprio 1 for waves 4-7 during the attention phase (restored to 0 at exit), on top of previous GEMM loop edits
# baseline (speedup 1.0000x reference)
; #define LAS __attribute__((address_space(3)))
; __global__ void __launch_bounds__(512, 2) mk_fwd(Args args) {
;     ...
;           { PH_IDS unsigned char* ws = WS_; const bf16* P = (const bf16*)(ws + WS_P); bf16* OB = (bf16*)(ws + WS_O);
;             for (;;) {
;               if (tid == 0) ((volatile LAS unsigned*)(lds + LDS_BARST + 64))[0] = __hip_atomic_fetch_add((unsigned*)(WS_ + WS_BAR + 16384) + (l * 2 + rep_) * 64, 1u, __ATOMIC_RELAXED, __HIP_MEMORY_SCOPE_AGENT);
;               __syncthreads();
;               const int item = __builtin_amdgcn_readfirstlane((int)((volatile LAS unsigned*)(lds + LDS_BARST + 64))[0]);
;               if (item >= 768) break;
;               const int hm = item % 12, qb = 63 - item / 12;
;               const attn_body::bf16* Qp = (const attn_body::bf16*)(P + C_DQ + hm * 64); const attn_body::bf16* Kp = (const attn_body::bf16*)(P + C_DK + hm * 64);
;               const attn_body::bf16* Vp = (const attn_body::bf16*)(P + C_DV + (hm >> 1) * 128); attn_body::bf16* Op = (attn_body::bf16*)(OB + hm * 128);
;               attn_body::attn_unit<8>(qb, Qp, Kp, Vp, Op, (char*)lds_raw); } }
.LBB0_210:
	s_or_b64 exec, exec, s[0:1]
	v_mov_b32_e32 v2, v230
	s_mov_b32 s0, s20
	s_waitcnt lgkmcnt(0)
	s_barrier
	s_mov_b32 s0, s26
	s_add_i32 s0, 0, 0x23088
	v_mov_b32_e32 v232, s0
	ds_read_b64 v[0:1], v232
	v_cmp_eq_u32_e64 s[2:3], 0, v2
	v_readfirstlane_b32 s84, v230
	s_cmp_lt_u32 s84, 0x100
	s_cbranch_scc1 .Lattn_prio_skip_0
	s_setprio 1
.Lattn_prio_skip_0:
	v_mov_b32_e32 v233, 0x35084000
	v_mov_b32_e32 v221, 0
	s_movk_i32 s66, 0x6000
	s_waitcnt lgkmcnt(0)
	v_readfirstlane_b32 s0, v0
	v_readfirstlane_b32 s1, v1
	s_add_u32 s33, s0, 0x2be00000
	s_addc_u32 s58, s1, 0
	s_add_u32 s59, s0, 0x1c600800
	s_addc_u32 s60, s1, 0
	s_add_u32 s61, s0, 0x1c600e00
	s_addc_u32 s62, s1, 0
	s_add_u32 s63, s0, 0x1c601400
	s_addc_u32 s64, s1, 0
	s_add_i32 s65, 0, 0x23140
	v_mov_b32_e32 v234, s65
	s_mov_b64 s[8:9], 0x80
	s_mov_b64 s[10:11], 0xb8000
	s_mov_b64 s[12:13], 0x170000
	s_mov_b32 s67, 0x12000
	s_mov_b64 s[14:15], 0x228000
	s_mov_b64 s[16:17], 0xb8080
	s_mov_b32 s68, 0xc000
	s_mov_b64 s[22:23], 0x2e0000
	s_mov_b64 s[24:25], 0x1c771400
	s_mov_b64 s[28:29], 0x1c771480
	s_mov_b32 s69, 0x41000000
	s_mov_b64 s[30:31], 0x398000
	s_mov_b64 s[34:35], 0x1c829400
	s_mov_b64 s[36:37], 0x1c829480
	s_mov_b64 s[38:39], 0x1c6b9400
	s_mov_b64 s[40:41], 0x1c6b9480
	s_mov_b64 s[42:43], 0x6000
	s_mov_b64 s[44:45], 0xc000
	s_mov_b64 s[46:47], 0x12000
	v_mov_b32_e32 v235, 0xff800000
	s_branch .LBB0_213

; #define INP_(k) ((const float*)GETP(k))
; __device__ __forceinline__ void g1_load(G1Pre& p, const bf16* P, const float* w2, const float* gb, int unit, int tid) {
;     const int c = unit >> 2, h = unit & 3, j = tid & 63, cg_ = tid >> 6; const bf16* Pc = P + (size_t)(c * 64) * INP;
; #pragma unroll
;     for (int rr = 0; rr < 2; ++rr) { const int c8 = cg_ + 8 * rr; p.k[rr] = c8 < 12 ? *(const v4u*)(Pc + (size_t)j * INP + C_GK + h * 96 + c8 * 8) : (v4u){0u, 0u, 0u, 0u}; }
; #pragma unroll
;     for (int rr = 0; rr < 3; ++rr) { const int c8 = cg_ + 8 * rr; p.v[rr] = *(const v4u*)(Pc + (size_t)j * INP + C_GV + h * 192 + c8 * 8); }
;     p.gc = tid < 128 ? *(const v4u*)(Pc + (size_t)(tid >> 1) * INP + C_GC + (tid & 1) * 8) : (v4u){0u, 0u, 0u, 0u};
; __global__ void __launch_bounds__(512, 2) mk_fwd(Args args) {
;     ...
;           { PH_IDS unsigned char* ws = WS_; const bf16* P = (const bf16*)(ws + WS_P); const float* w2 = INP_(8) + l * 16 * 384; const float* gb = INP_(9) + l * 384;
;             G1Pre ca; if (bid < 1024) g1_load(ca, P, w2, gb, bid, tid);
.LBB0_298:
	s_setprio 0
	s_add_i32 s0, 0, 0x23088
	v_mov_b32_e32 v40, v230
	s_mov_b32 s48, s20
	s_mov_b32 s33, s26
	v_mov_b32_e32 v0, s0
	s_barrier
	ds_read_b64 v[0:1], v0
	s_mov_b32 s5, 0
	v_and_b32_e32 v18, 63, v40
	v_ashrrev_i32_e32 v41, 6, v40
	s_waitcnt lgkmcnt(0)
	v_readfirstlane_b32 s9, v0
	v_readfirstlane_b32 s8, v1
	s_add_u32 s46, s9, 0x1c600000
	s_addc_u32 s47, s8, 0
	s_add_i32 s0, 0, 0x23040
	v_mov_b32_e32 v0, s0
	s_add_i32 s0, 0, 0x23048
	v_mov_b32_e32 v2, s0
	ds_read_b64 v[0:1], v0
	ds_read_b64 v[2:3], v2
	s_cmpk_lt_i32 s48, 0x400
	s_cselect_b64 s[0:1], -1, 0
	s_and_b64 vcc, exec, s[0:1]
	s_waitcnt lgkmcnt(1)
	v_readfirstlane_b32 s23, v1
	v_readfirstlane_b32 s22, v0
	s_waitcnt lgkmcnt(0)
	v_readfirstlane_b32 s25, v3
	v_readfirstlane_b32 s24, v2
	s_cbranch_vccz .LBB0_312
	s_lshl_b32 s2, s48, 4
	s_andn2_b32 s2, s2, 63
	s_and_b32 s11, s48, 3
	s_mul_hi_i32 s3, s2, 0x2e00
	s_mulk_i32 s2, 0x2e00
	s_add_u32 s2, s46, s2
	v_mul_u32_u24_e32 v0, 0x1700, v18
	v_mov_b32_e32 v28, 0
	s_addc_u32 s3, s47, s3
	v_lshlrev_b32_e32 v0, 1, v0
	v_mov_b32_e32 v1, v28
	s_mul_i32 s10, s11, 0x60
	v_lshl_add_u64 v[4:5], s[2:3], 0, v[0:1]
	s_lshl_b32 s4, s10, 1
	v_lshl_add_u64 v[0:1], v[4:5], 0, s[4:5]
	s_mov_b64 s[6:7], 0x1d00
	v_cmp_lt_i32_e32 vcc, 11, v41
	v_lshlrev_b32_e32 v6, 3, v41
	s_and_saveexec_b64 s[4:5], vcc
	s_xor_b64 s[4:5], exec, s[4:5]
	v_lshlrev_b32_e32 v6, 3, v41
	s_or_saveexec_b64 s[4:5], s[4:5]
	v_lshl_add_u64 v[8:9], v[0:1], 0, s[6:7]
	v_mov_b32_e32 v29, v28
	v_mov_b32_e32 v30, v28
	v_mov_b32_e32 v31, v28
	s_xor_b64 exec, exec, s[4:5]
	s_cbranch_execz .LBB0_303
	v_ashrrev_i32_e32 v7, 31, v6
	v_lshl_add_u64 v[0:1], v[6:7], 1, v[8:9]
	global_load_dwordx4 v[28:31], v[0:1], off

; #define LAS __attribute__((address_space(3)))
; __global__ void __launch_bounds__(512, 2) mk_fwd(Args args) {
;     ...
;           { PH_IDS unsigned char* ws = WS_; const bf16* P = (const bf16*)(ws + WS_P); bf16* OB = (bf16*)(ws + WS_O);
;             for (;;) {
;               if (tid == 0) ((volatile LAS unsigned*)(lds + LDS_BARST + 64))[0] = __hip_atomic_fetch_add((unsigned*)(WS_ + WS_BAR + 16384) + (l * 2 + rep_) * 64, 1u, __ATOMIC_RELAXED, __HIP_MEMORY_SCOPE_AGENT);
;               __syncthreads();
;               const int item = __builtin_amdgcn_readfirstlane((int)((volatile LAS unsigned*)(lds + LDS_BARST + 64))[0]);
;               if (item >= 768) break;
;               const int hm = item % 12, qb = 63 - item / 12;
;               const attn_body::bf16* Qp = (const attn_body::bf16*)(P + C_DQ + hm * 64); const attn_body::bf16* Kp = (const attn_body::bf16*)(P + C_DK + hm * 64);
;               const attn_body::bf16* Vp = (const attn_body::bf16*)(P + C_DV + (hm >> 1) * 128); attn_body::bf16* Op = (attn_body::bf16*)(OB + hm * 128);
;               attn_body::attn_unit<8>(qb, Qp, Kp, Vp, Op, (char*)lds_raw); } }
.LBB0_932:
	s_or_b64 exec, exec, s[0:1]
	v_mov_b32_e32 v2, v230
	s_mov_b32 s0, s20
	s_waitcnt lgkmcnt(0)
	s_barrier
	s_mov_b32 s0, s26
	s_add_i32 s0, 0, 0x23088
	v_mov_b32_e32 v237, s0
	ds_read_b64 v[0:1], v237
	v_cmp_eq_u32_e64 s[2:3], 0, v2
	v_readfirstlane_b32 s84, v230
	s_cmp_lt_u32 s84, 0x100
	s_cbranch_scc1 .Lattn_prio_skip_1
	s_setprio 1
.Lattn_prio_skip_1:
	v_mov_b32_e32 v238, 0x35084000
	v_mov_b32_e32 v221, 0
	s_movk_i32 s66, 0x6000
	s_waitcnt lgkmcnt(0)
	v_readfirstlane_b32 s0, v0
	v_readfirstlane_b32 s1, v1
	s_add_u32 s33, s0, 0x2be00000
	s_addc_u32 s58, s1, 0
	s_add_u32 s59, s0, 0x1c600800
	s_addc_u32 s60, s1, 0
	s_add_u32 s61, s0, 0x1c600e00
	s_addc_u32 s62, s1, 0
	s_add_u32 s63, s0, 0x1c601400
	s_addc_u32 s64, s1, 0
	s_add_i32 s65, 0, 0x23140
	v_mov_b32_e32 v239, s65
	s_mov_b64 s[8:9], 0x80
	s_mov_b64 s[10:11], 0xb8000
	s_mov_b64 s[12:13], 0x170000
	s_mov_b32 s67, 0x12000
	s_mov_b64 s[14:15], 0x228000
	s_mov_b64 s[16:17], 0xb8080
	s_mov_b32 s68, 0xc000
	s_mov_b64 s[22:23], 0x2e0000
	s_mov_b64 s[24:25], 0x1c771400
	s_mov_b64 s[28:29], 0x1c771480
	s_mov_b32 s69, 0x41000000
	s_mov_b64 s[30:31], 0x398000
	s_mov_b64 s[34:35], 0x1c829400
	s_mov_b64 s[36:37], 0x1c829480
	s_mov_b64 s[38:39], 0x1c6b9400
	s_mov_b64 s[40:41], 0x1c6b9480
	s_mov_b64 s[42:43], 0x6000
	s_mov_b64 s[44:45], 0xc000
	s_mov_b64 s[46:47], 0x12000
	v_mov_b32_e32 v240, 0xff800000
	s_branch .LBB0_935

; #define INP_(k) ((const float*)GETP(k))
; __device__ __forceinline__ void g1_load(G1Pre& p, const bf16* P, const float* w2, const float* gb, int unit, int tid) {
;     const int c = unit >> 2, h = unit & 3, j = tid & 63, cg_ = tid >> 6; const bf16* Pc = P + (size_t)(c * 64) * INP;
; #pragma unroll
;     for (int rr = 0; rr < 2; ++rr) { const int c8 = cg_ + 8 * rr; p.k[rr] = c8 < 12 ? *(const v4u*)(Pc + (size_t)j * INP + C_GK + h * 96 + c8 * 8) : (v4u){0u, 0u, 0u, 0u}; }
; #pragma unroll
;     for (int rr = 0; rr < 3; ++rr) { const int c8 = cg_ + 8 * rr; p.v[rr] = *(const v4u*)(Pc + (size_t)j * INP + C_GV + h * 192 + c8 * 8); }
;     p.gc = tid < 128 ? *(const v4u*)(Pc + (size_t)(tid >> 1) * INP + C_GC + (tid & 1) * 8) : (v4u){0u, 0u, 0u, 0u};
; __global__ void __launch_bounds__(512, 2) mk_fwd(Args args) {
;     ...
;           { PH_IDS unsigned char* ws = WS_; const bf16* P = (const bf16*)(ws + WS_P); const float* w2 = INP_(8) + l * 16 * 384; const float* gb = INP_(9) + l * 384;
;             G1Pre ca; if (bid < 1024) g1_load(ca, P, w2, gb, bid, tid);
.LBB0_1020:
	s_setprio 0
	s_add_i32 s0, 0, 0x23088
	v_mov_b32_e32 v40, v230
	s_mov_b32 s48, s20
	s_mov_b32 s33, s26
	v_mov_b32_e32 v0, s0
	s_barrier
	ds_read_b64 v[0:1], v0
	s_mov_b32 s5, 0
	v_and_b32_e32 v18, 63, v40
	v_ashrrev_i32_e32 v41, 6, v40
	s_waitcnt lgkmcnt(0)
	v_readfirstlane_b32 s9, v0
	v_readfirstlane_b32 s8, v1
	s_add_u32 s46, s9, 0x1c600000
	s_addc_u32 s47, s8, 0
	s_add_i32 s0, 0, 0x23040
	v_mov_b32_e32 v0, s0
	ds_read_b64 v[0:1], v0
	s_waitcnt lgkmcnt(0)
	v_readfirstlane_b32 s1, v0
	v_readfirstlane_b32 s0, v1
	s_add_u32 s22, s1, 0x6000
	s_addc_u32 s23, s0, 0
	s_add_i32 s0, 0, 0x23048
	v_mov_b32_e32 v0, s0
	ds_read_b64 v[0:1], v0
	s_cmpk_lt_i32 s48, 0x400
	s_cselect_b64 s[0:1], -1, 0
	s_and_b64 vcc, exec, s[0:1]
	s_waitcnt lgkmcnt(0)
	v_readfirstlane_b32 s25, v1
	v_readfirstlane_b32 s24, v0
	s_cbranch_vccz .LBB0_1034
	s_lshl_b32 s2, s48, 4
	s_andn2_b32 s2, s2, 63
	s_and_b32 s11, s48, 3
	s_mul_hi_i32 s3, s2, 0x2e00
	s_mulk_i32 s2, 0x2e00
	s_add_u32 s2, s46, s2
	v_mul_u32_u24_e32 v0, 0x1700, v18
	v_mov_b32_e32 v28, 0
	s_addc_u32 s3, s47, s3
	v_lshlrev_b32_e32 v0, 1, v0
	v_mov_b32_e32 v1, v28
	s_mul_i32 s10, s11, 0x60
	v_lshl_add_u64 v[4:5], s[2:3], 0, v[0:1]
	s_lshl_b32 s4, s10, 1
	v_lshl_add_u64 v[0:1], v[4:5], 0, s[4:5]
	s_mov_b64 s[6:7], 0x1d00
	v_cmp_lt_i32_e32 vcc, 11, v41
	v_lshlrev_b32_e32 v6, 3, v41
	s_and_saveexec_b64 s[4:5], vcc
	s_xor_b64 s[4:5], exec, s[4:5]
	v_lshlrev_b32_e32 v6, 3, v41
	s_or_saveexec_b64 s[4:5], s[4:5]
	v_lshl_add_u64 v[8:9], v[0:1], 0, s[6:7]
	v_mov_b32_e32 v29, v28
	v_mov_b32_e32 v30, v28
	v_mov_b32_e32 v31, v28
	s_xor_b64 exec, exec, s[4:5]
	s_cbranch_execz .LBB0_1025
	v_ashrrev_i32_e32 v7, 31, v6
	v_lshl_add_u64 v[0:1], v[6:7], 1, v[8:9]
	global_load_dwordx4 v[28:31], v[0:1], off

; #define INP_(k) ((const float*)GETP(k))
; __device__ __forceinline__ void g1_load(G1Pre& p, const bf16* P, const float* w2, const float* gb, int unit, int tid) {
;     const int c = unit >> 2, h = unit & 3, j = tid & 63, cg_ = tid >> 6; const bf16* Pc = P + (size_t)(c * 64) * INP;
; #pragma unroll
;     for (int rr = 0; rr < 2; ++rr) { const int c8 = cg_ + 8 * rr; p.k[rr] = c8 < 12 ? *(const v4u*)(Pc + (size_t)j * INP + C_GK + h * 96 + c8 * 8) : (v4u){0u, 0u, 0u, 0u}; }
; #pragma unroll
;     for (int rr = 0; rr < 3; ++rr) { const int c8 = cg_ + 8 * rr; p.v[rr] = *(const v4u*)(Pc + (size_t)j * INP + C_GV + h * 192 + c8 * 8); }
;     p.gc = tid < 128 ? *(const v4u*)(Pc + (size_t)(tid >> 1) * INP + C_GC + (tid & 1) * 8) : (v4u){0u, 0u, 0u, 0u};
; __global__ void __launch_bounds__(512, 2) mk_fwd(Args args) {
;     ...
;           { PH_IDS unsigned char* ws = WS_; const bf16* P = (const bf16*)(ws + WS_P); const float* w2 = INP_(8) + l * 16 * 384; const float* gb = INP_(9) + l * 384;
;             G1Pre ca; if (bid < 1024) g1_load(ca, P, w2, gb, bid, tid);
.LBB0_1742:
	s_setprio 0
	s_add_i32 s0, 0, 0x23088
	v_mov_b32_e32 v40, v230
	s_mov_b32 s48, s20
	s_mov_b32 s33, s26
	v_mov_b32_e32 v0, s0
	s_barrier
	ds_read_b64 v[0:1], v0
	s_mov_b32 s5, 0
	v_and_b32_e32 v22, 63, v40
	v_ashrrev_i32_e32 v41, 6, v40
	s_waitcnt lgkmcnt(0)
	v_readfirstlane_b32 s9, v0
	v_readfirstlane_b32 s8, v1
	s_add_u32 s46, s9, 0x1c600000
	s_addc_u32 s47, s8, 0
	s_add_i32 s0, 0, 0x23040
	v_mov_b32_e32 v0, s0
	ds_read_b64 v[0:1], v0
	s_waitcnt lgkmcnt(0)
	v_readfirstlane_b32 s1, v0
	v_readfirstlane_b32 s0, v1
	s_add_u32 s22, s1, 0xc000
	s_addc_u32 s23, s0, 0
	s_add_i32 s0, 0, 0x23048
	v_mov_b32_e32 v0, s0
	ds_read_b64 v[0:1], v0
	s_cmpk_lt_i32 s48, 0x400
	s_cselect_b64 s[0:1], -1, 0
	s_and_b64 vcc, exec, s[0:1]
	s_waitcnt lgkmcnt(0)
	v_readfirstlane_b32 s25, v1
	v_readfirstlane_b32 s24, v0
	s_cbranch_vccz .LBB0_1756
	s_lshl_b32 s2, s48, 4
	s_andn2_b32 s2, s2, 63
	s_and_b32 s11, s48, 3
	s_mul_hi_i32 s3, s2, 0x2e00
	s_mulk_i32 s2, 0x2e00
	s_add_u32 s2, s46, s2
	v_mul_u32_u24_e32 v0, 0x1700, v22
	v_mov_b32_e32 v24, 0
	s_addc_u32 s3, s47, s3
	v_lshlrev_b32_e32 v0, 1, v0
	v_mov_b32_e32 v1, v24
	s_mul_i32 s10, s11, 0x60
	v_lshl_add_u64 v[4:5], s[2:3], 0, v[0:1]
	s_lshl_b32 s4, s10, 1
	v_lshl_add_u64 v[0:1], v[4:5], 0, s[4:5]
	s_mov_b64 s[6:7], 0x1d00
	v_cmp_lt_i32_e32 vcc, 11, v41
	v_lshlrev_b32_e32 v6, 3, v41
	s_and_saveexec_b64 s[4:5], vcc
	s_xor_b64 s[4:5], exec, s[4:5]
	v_lshlrev_b32_e32 v6, 3, v41
	s_or_saveexec_b64 s[4:5], s[4:5]
	v_lshl_add_u64 v[8:9], v[0:1], 0, s[6:7]
	v_mov_b32_e32 v25, v24
	v_mov_b32_e32 v26, v24
	v_mov_b32_e32 v27, v24
	s_xor_b64 exec, exec, s[4:5]
	s_cbranch_execz .LBB0_1747
	v_ashrrev_i32_e32 v7, 31, v6
	v_lshl_add_u64 v[0:1], v[6:7], 1, v[8:9]
	global_load_dwordx4 v[24:27], v[0:1], off

; #define INP_(k) ((const float*)GETP(k))
; __device__ __forceinline__ void g1_load(G1Pre& p, const bf16* P, const float* w2, const float* gb, int unit, int tid) {
;     const int c = unit >> 2, h = unit & 3, j = tid & 63, cg_ = tid >> 6; const bf16* Pc = P + (size_t)(c * 64) * INP;
; #pragma unroll
;     for (int rr = 0; rr < 2; ++rr) { const int c8 = cg_ + 8 * rr; p.k[rr] = c8 < 12 ? *(const v4u*)(Pc + (size_t)j * INP + C_GK + h * 96 + c8 * 8) : (v4u){0u, 0u, 0u, 0u}; }
; #pragma unroll
;     for (int rr = 0; rr < 3; ++rr) { const int c8 = cg_ + 8 * rr; p.v[rr] = *(const v4u*)(Pc + (size_t)j * INP + C_GV + h * 192 + c8 * 8); }
;     p.gc = tid < 128 ? *(const v4u*)(Pc + (size_t)(tid >> 1) * INP + C_GC + (tid & 1) * 8) : (v4u){0u, 0u, 0u, 0u};
; __global__ void __launch_bounds__(512, 2) mk_fwd(Args args) {
;     ...
;           { PH_IDS unsigned char* ws = WS_; const bf16* P = (const bf16*)(ws + WS_P); const float* w2 = INP_(8) + l * 16 * 384; const float* gb = INP_(9) + l * 384;
;             G1Pre ca; if (bid < 1024) g1_load(ca, P, w2, gb, bid, tid);
.LBB0_2464:
	s_setprio 0
	s_add_i32 s0, 0, 0x23088
	v_mov_b32_e32 v40, v230
	s_mov_b32 s48, s20
	s_mov_b32 s33, s26
	v_mov_b32_e32 v0, s0
	s_barrier
	ds_read_b64 v[0:1], v0
	s_mov_b32 s5, 0
	v_and_b32_e32 v22, 63, v40
	v_ashrrev_i32_e32 v41, 6, v40
	s_waitcnt lgkmcnt(0)
	v_readfirstlane_b32 s9, v0
	v_readfirstlane_b32 s8, v1
	s_add_u32 s46, s9, 0x1c600000
	s_addc_u32 s47, s8, 0
	s_add_i32 s0, 0, 0x23040
	v_mov_b32_e32 v0, s0
	ds_read_b64 v[0:1], v0
	s_waitcnt lgkmcnt(0)
	v_readfirstlane_b32 s1, v0
	v_readfirstlane_b32 s0, v1
	s_add_u32 s22, s1, 0x12000
	s_addc_u32 s23, s0, 0
	s_add_i32 s0, 0, 0x23048
	v_mov_b32_e32 v0, s0
	ds_read_b64 v[0:1], v0
	s_waitcnt lgkmcnt(0)
	v_readfirstlane_b32 s1, v0
	v_readfirstlane_b32 s0, v1
	s_add_u32 s24, s1, 0x1200
	s_addc_u32 s25, s0, 0
	s_cmpk_lt_i32 s48, 0x400
	s_cselect_b64 s[0:1], -1, 0
	s_and_b64 vcc, exec, s[0:1]
	s_cbranch_vccz .LBB0_2478
	s_lshl_b32 s2, s48, 4
	s_andn2_b32 s2, s2, 63
	s_and_b32 s11, s48, 3
	s_mul_hi_i32 s3, s2, 0x2e00
	s_mulk_i32 s2, 0x2e00
	s_add_u32 s2, s46, s2
	v_mul_u32_u24_e32 v0, 0x1700, v22
	v_mov_b32_e32 v24, 0
	s_addc_u32 s3, s47, s3
	v_lshlrev_b32_e32 v0, 1, v0
	v_mov_b32_e32 v1, v24
	s_mul_i32 s10, s11, 0x60
	v_lshl_add_u64 v[4:5], s[2:3], 0, v[0:1]
	s_lshl_b32 s4, s10, 1
	v_lshl_add_u64 v[0:1], v[4:5], 0, s[4:5]
	s_mov_b64 s[6:7], 0x1d00
	v_cmp_lt_i32_e32 vcc, 11, v41
	v_lshlrev_b32_e32 v6, 3, v41
	s_and_saveexec_b64 s[4:5], vcc
	s_xor_b64 s[4:5], exec, s[4:5]
	v_lshlrev_b32_e32 v6, 3, v41
	s_or_saveexec_b64 s[4:5], s[4:5]
	v_lshl_add_u64 v[8:9], v[0:1], 0, s[6:7]
	v_mov_b32_e32 v25, v24
	v_mov_b32_e32 v26, v24
	v_mov_b32_e32 v27, v24
	s_xor_b64 exec, exec, s[4:5]
	s_cbranch_execz .LBB0_2469
	v_ashrrev_i32_e32 v7, 31, v6
	v_lshl_add_u64 v[0:1], v[6:7], 1, v[8:9]
	global_load_dwordx4 v[24:27], v[0:1], off

; __global__ void __launch_bounds__(512, 2) mk_fwd(Args args) {
	.amdhsa_kernel _Z6mk_fwd4Args
		.amdhsa_group_segment_fixed_size 0
		.amdhsa_private_segment_fixed_size 0
		.amdhsa_kernarg_size 400
		.amdhsa_user_sgpr_count 2
		.amdhsa_user_sgpr_dispatch_ptr 0
		.amdhsa_user_sgpr_queue_ptr 0
		.amdhsa_user_sgpr_kernarg_segment_ptr 1
		.amdhsa_user_sgpr_dispatch_id 0
		.amdhsa_user_sgpr_kernarg_preload_length 0
		.amdhsa_user_sgpr_kernarg_preload_offset 0
		.amdhsa_user_sgpr_private_segment_size 0
		.amdhsa_uses_dynamic_stack 0
		.amdhsa_enable_private_segment 0
		.amdhsa_system_sgpr_workgroup_id_x 1
		.amdhsa_system_sgpr_workgroup_id_y 0
		.amdhsa_system_sgpr_workgroup_id_z 0
		.amdhsa_system_sgpr_workgroup_info 0
		.amdhsa_system_vgpr_workitem_id 2
		.amdhsa_next_free_vgpr 254
		.amdhsa_next_free_sgpr 96
		.amdhsa_accum_offset 256
		.amdhsa_reserve_vcc 1
		.amdhsa_float_round_mode_32 0
		.amdhsa_float_round_mode_16_64 0
		.amdhsa_float_denorm_mode_32 3
		.amdhsa_float_denorm_mode_16_64 3
		.amdhsa_dx10_clamp 1
		.amdhsa_ieee_mode 1
		.amdhsa_fp16_overflow 0
		.amdhsa_tg_split 0
		.amdhsa_exception_fp_ieee_invalid_op 0
		.amdhsa_exception_fp_denorm_src 0
		.amdhsa_exception_fp_ieee_div_zero 0
		.amdhsa_exception_fp_ieee_overflow 0
		.amdhsa_exception_fp_ieee_underflow 0
		.amdhsa_exception_fp_ieee_inexact 0
		.amdhsa_exception_int_div_zero 0
	.end_amdhsa_kernel

; __global__ void __launch_bounds__(512, 2) mk_fwd(Args args) {
amdhsa.kernels:
  - .agpr_count:     0
    .args:
      - .offset:         0
        .size:           144
        .value_kind:     by_value
      - .offset:         144
        .size:           4
        .value_kind:     hidden_block_count_x
      - .offset:         148
        .size:           4
        .value_kind:     hidden_block_count_y
      - .offset:         152
        .size:           4
        .value_kind:     hidden_block_count_z
      - .offset:         156
        .size:           2
        .value_kind:     hidden_group_size_x
      - .offset:         158
        .size:           2
        .value_kind:     hidden_group_size_y
      - .offset:         160
        .size:           2
        .value_kind:     hidden_group_size_z
      - .offset:         162
        .size:           2
        .value_kind:     hidden_remainder_x
      - .offset:         164
        .size:           2
        .value_kind:     hidden_remainder_y
      - .offset:         166
        .size:           2
        .value_kind:     hidden_remainder_z
      - .offset:         184
        .size:           8
        .value_kind:     hidden_global_offset_x
      - .offset:         192
        .size:           8
        .value_kind:     hidden_global_offset_y
      - .offset:         200
        .size:           8
        .value_kind:     hidden_global_offset_z
      - .offset:         208
        .size:           2
        .value_kind:     hidden_grid_dims
      - .offset:         232
        .size:           8
        .value_kind:     hidden_multigrid_sync_arg
      - .offset:         264
        .size:           4
        .value_kind:     hidden_dynamic_lds_size
    .group_segment_fixed_size: 0
    .kernarg_segment_align: 8
    .kernarg_segment_size: 400
    .language:       OpenCL C
    .language_version:
      - 2
      - 0
    .max_flat_workgroup_size: 512
    .name:           _Z6mk_fwd4Args
    .private_segment_fixed_size: 0
    .sgpr_count:     102
    .sgpr_spill_count: 0
    .symbol:         _Z6mk_fwd4Args.kd
    .uniform_work_group_size: 1
    .uses_dynamic_stack: false
    .vgpr_count:     254
    .vgpr_spill_count: 0
    .wavefront_size: 64
